# P0 job loop: next-item L2 prefetch (one-dword touch of the lines the same workgroup's next w_out transpose / w_query convert item reads), on top of v121
# speedup vs baseline: 1.0007x; 1.0007x over previous
.LBB0_77:
	s_andn2_b64 vcc, exec, s[0:1]
	s_cbranch_vccnz .LBB0_79
	v_lshl_add_u32 v26, s22, 12, v99
	v_ashrrev_i32_e32 v27, 31, v26
	v_lshl_add_u64 v[22:23], v[26:27], 2, s[48:49]
	global_load_dwordx4 v[2:5], v[22:23], off
	s_cmpk_lt_u32 s22, 0xcc0
	s_cbranch_scc0 .Lpf0_wq
	v_add_co_u32_e32 v242, vcc, 0x400000, v22
	s_nop 1
	v_addc_co_u32_e32 v243, vcc, 0, v23, vcc
	global_load_dword v241, v[242:243], off
.Lpf0_wq:
	s_nop 0
	global_load_dwordx4 v[22:25], v[22:23], off offset:16
	s_waitcnt vmcnt(1)
	v_cvt_pk_bf16_f32 v2, v2, v3
	v_cvt_pk_bf16_f32 v3, v4, v5
	s_waitcnt vmcnt(0)
	v_cvt_pk_bf16_f32 v4, v22, v23
	v_lshl_add_u64 v[22:23], v[26:27], 1, s[34:35]
	v_cvt_pk_bf16_f32 v5, v24, v25
	global_store_dwordx4 v[22:23], v[2:5], off

.LBB0_80:
	s_andn2_b64 vcc, exec, s[0:1]
	s_cbranch_vccnz .LBB0_82
	v_mov_b32_e32 v2, v156
	s_lshl_b32 s0, s22, 1
	s_and_b32 s0, s0, 0x1fc0
	v_ashrrev_i32_e32 v11, 3, v2
	v_lshlrev_b32_e32 v2, 3, v2
	s_addk_i32 s0, 0xf480
	v_and_b32_e32 v26, 56, v2
	v_add_u32_e32 v2, s0, v11
	v_ashrrev_i32_e32 v3, 31, v2
	s_lshl_b32 s1, s22, 6
	v_lshlrev_b64 v[2:3], 13, v[2:3]
	s_and_b32 s6, s1, 0x7c0
	v_lshl_add_u64 v[2:3], s[44:45], 0, v[2:3]
	s_lshl_b32 s50, s6, 2
	v_lshl_add_u64 v[2:3], v[2:3], 0, s[50:51]
	v_lshlrev_b32_e32 v6, 2, v26
	v_lshl_add_u64 v[22:23], v[2:3], 0, v[6:7]
	s_barrier
	global_load_dwordx4 v[2:5], v[22:23], off nt
	s_cmpk_lt_u32 s22, 0x8c0
	s_cbranch_scc0 .Lpf0_wout
	v_add_co_u32_e32 v242, vcc, 0x400000, v22
	s_nop 1
	v_addc_co_u32_e32 v243, vcc, 0, v23, vcc
	global_load_dword v241, v[242:243], off
.Lpf0_wout:
	s_nop 0
	global_load_dwordx4 v[22:25], v[22:23], off offset:16 nt
	v_mul_lo_u32 v27, v11, s14
	v_lshlrev_b32_e32 v28, 2, v11
	v_mul_u32_u24_e32 v29, 0x104, v26
	v_add3_u32 v6, 0, v27, v6
	v_add3_u32 v27, 0, v29, v28
	s_mov_b32 s1, s51
	s_waitcnt vmcnt(1)
	ds_write2_b32 v6, v2, v3 offset1:1
	ds_write2_b32 v6, v4, v5 offset0:2 offset1:3
	s_waitcnt vmcnt(0)
	ds_write2_b32 v6, v22, v23 offset0:4 offset1:5
	ds_write2_b32 v6, v24, v25 offset0:6 offset1:7
	v_add_u32_e32 v22, s6, v11
	s_waitcnt lgkmcnt(0)
	s_barrier
	ds_read2_b32 v[2:3], v27 offset1:65
	v_ashrrev_i32_e32 v23, 31, v22
	s_waitcnt lgkmcnt(0)
	v_cvt_pk_bf16_f32 v2, v2, v3
	ds_read2_b32 v[4:5], v27 offset0:130 offset1:195
	v_add_u32_e32 v6, 0x400, v27
	v_lshlrev_b64 v[22:23], 12, v[22:23]
	s_waitcnt lgkmcnt(0)
	v_cvt_pk_bf16_f32 v3, v4, v5
	ds_read2_b32 v[4:5], v6 offset0:4 offset1:69
	v_lshl_add_u64 v[22:23], s[16:17], 0, v[22:23]
	s_waitcnt lgkmcnt(0)
	v_cvt_pk_bf16_f32 v4, v4, v5
	ds_read2_b32 v[24:25], v6 offset0:134 offset1:199
	v_lshl_add_u64 v[22:23], s[0:1], 1, v[22:23]
	v_lshlrev_b32_e32 v6, 1, v26
	v_lshl_add_u64 v[22:23], v[22:23], 0, v[6:7]
	s_waitcnt lgkmcnt(0)
	v_cvt_pk_bf16_f32 v5, v24, v25
	global_store_dwordx4 v[22:23], v[2:5], off
